# GEMM load segments: the 8 A-fragment LDS reads with loop-invariant address issue first after each barrier, ahead of scalar/address setup
# baseline (speedup 1.0000x reference)
; #define PG8_STAGE(bufoff, gbase, voff) do { _Pragma("unroll") for (int _i = 0; _i < 2; ++_i) \
;         __builtin_amdgcn_global_load_lds((const unsigned*)((const char*)(gbase) + (voff)[_i]), (PG8_LAS unsigned*)(lds + (bufoff) + ldsw + _i * 8192), 16, 0, 0); } while (0)
; #define PG8_LDA(dst, b, h) do { _Pragma("unroll") for (int m = 0; m < 4; ++m) _Pragma("unroll") for (int k = 0; k < 2; ++k) dst[m][k] = *(const PG8_LAS bf16x8*)(lds + PG8_SA(b, h) + aoff + m * 2048 + k * 1024); } while (0)
; #define PG8_LDB(dst, b, h) do { _Pragma("unroll") for (int n = 0; n < 2; ++n) _Pragma("unroll") for (int k = 0; k < 2; ++k) dst[n][k] = *(const PG8_LAS bf16x8*)(lds + PG8_SB(b, h) + boff + n * 2048 + k * 1024); } while (0)
; #define PG8_MMA(ai, bj, At, Bt) do { __builtin_amdgcn_s_setprio(1); _Pragma("unroll") for (int m = 0; m < 4; ++m) _Pragma("unroll") for (int n = 0; n < 2; ++n) _Pragma("unroll") for (int k = 0; k < 2; ++k) \
;         acc[ai][bj][m][n] = __builtin_amdgcn_mfma_f32_16x16x32_bf16(Bt[n][k], At[m][k], acc[ai][bj][m][n], 0, 0, 0); __builtin_amdgcn_s_setprio(0); } while (0)
; #define PG8_WAIT_V(n) asm volatile("s_waitcnt vmcnt(" #n ")" ::: "memory")
; #define PG8_WAIT_L(n) asm volatile("s_waitcnt lgkmcnt(" #n ")" ::: "memory")
; #define PG8_BAR __builtin_amdgcn_s_barrier()
; #define PG8_SCHED __builtin_amdgcn_sched_barrier(0)
; template <class Epi, class Sched, bool ALIGN_EPI = false, bool SP2 = false>
; __device__ __forceinline__ void gemm_phase(PG8_LAS unsigned char* lds, const Gemm g, const Sched& S, const Epi& E) {
;     ...
;             PG8_LDB(B0, 0, 0); PG8_LDB(B1, 0, 1); PG8_SCHED; PG8_LDA(At, 0, 0); PG8_STAGE(PG8_SA(1, 1), a1 + hstep, voffA);
;             PG8_WAIT_V(8); PG8_WAIT_L(0); PG8_BAR; PG8_MMA(0, 0, At, B0); PG8_MMA(0, 1, At, B1); PG8_BAR; PG8_SCHED;
;             PG8_LDA(At, 0, 1); PG8_STAGE(PG8_SB(0, 0), b2, voffB); PG8_STAGE(PG8_SB(0, 1), b2 + hstep, voffB); PG8_STAGE(PG8_SA(0, 0), a2, voffA);
.LBB0_436:
	ds_read_b128 v[176:179], v143
	ds_read_b128 v[180:183], v143 offset:1024
	ds_read_b128 v[184:187], v143 offset:2048
	ds_read_b128 v[188:191], v143 offset:3072
	ds_read_b128 v[192:195], v143 offset:4096
	ds_read_b128 v[196:199], v143 offset:5120
	ds_read_b128 v[200:203], v143 offset:6144
	ds_read_b128 v[204:207], v143 offset:7168
	s_add_u32 s16, s14, 0xfff80080
	s_addc_u32 s17, s15, -1
	s_add_i32 s48, 0, 0x10000
	s_cmp_eq_u32 s47, 28
	s_cselect_b32 s19, s9, s17
	s_cselect_b32 s18, s43, s16
	s_cselect_b32 s17, s7, s46
	s_cselect_b32 s16, s44, s45
	s_add_i32 s50, 0, 0x14000
	v_add_u32_e32 v156, s48, v140
	v_add_u32_e32 v172, s50, v140
	ds_read_b128 v[144:147], v156
	ds_read_b128 v[148:151], v156 offset:1024
	ds_read_b128 v[152:155], v156 offset:2048
	ds_read_b128 v[156:159], v156 offset:3072
	ds_read_b128 v[160:163], v172
	ds_read_b128 v[164:167], v172 offset:1024
	ds_read_b128 v[168:171], v172 offset:2048
	ds_read_b128 v[172:175], v172 offset:3072
	s_add_i32 m0, s23, 0xc000
	s_nop 0
	global_load_lds_dwordx4 v138, s[14:15]
	s_add_i32 m0, s23, 0xe000
	s_nop 0
	global_load_lds_dwordx4 v136, s[14:15]
	s_waitcnt vmcnt(8)
	s_waitcnt lgkmcnt(0)
	s_barrier
	s_setprio 1
	s_waitcnt lgkmcnt(0)
	v_mfma_f32_16x16x32_bf16 v[114:117], v[144:147], v[176:179], v[114:117]
	v_mfma_f32_16x16x32_bf16 v[118:121], v[152:155], v[176:179], v[118:121]
	v_mfma_f32_16x16x32_bf16 v[102:105], v[144:147], v[184:187], v[102:105]
	v_mfma_f32_16x16x32_bf16 v[106:109], v[152:155], v[184:187], v[106:109]
	v_mfma_f32_16x16x32_bf16 v[86:89], v[144:147], v[192:195], v[86:89]
	v_mfma_f32_16x16x32_bf16 v[82:85], v[152:155], v[192:195], v[82:85]
	v_mfma_f32_16x16x32_bf16 v[78:81], v[144:147], v[200:203], v[78:81]
	v_mfma_f32_16x16x32_bf16 v[58:61], v[152:155], v[200:203], v[58:61]
	v_mfma_f32_16x16x32_bf16 v[114:117], v[148:151], v[180:183], v[114:117]
	v_mfma_f32_16x16x32_bf16 v[118:121], v[156:159], v[180:183], v[118:121]
	v_mfma_f32_16x16x32_bf16 v[102:105], v[148:151], v[188:191], v[102:105]
	v_mfma_f32_16x16x32_bf16 v[106:109], v[156:159], v[188:191], v[106:109]
	v_mfma_f32_16x16x32_bf16 v[86:89], v[148:151], v[196:199], v[86:89]
	v_mfma_f32_16x16x32_bf16 v[82:85], v[156:159], v[196:199], v[82:85]
	v_mfma_f32_16x16x32_bf16 v[78:81], v[148:151], v[204:207], v[78:81]
	v_mfma_f32_16x16x32_bf16 v[58:61], v[156:159], v[204:207], v[58:61]
	s_setprio 0
	s_setprio 1
	v_mfma_f32_16x16x32_bf16 v[122:125], v[160:163], v[176:179], v[122:125]
	v_mfma_f32_16x16x32_bf16 v[126:129], v[168:171], v[176:179], v[126:129]
	v_mfma_f32_16x16x32_bf16 v[110:113], v[160:163], v[184:187], v[110:113]
	v_mfma_f32_16x16x32_bf16 v[98:101], v[168:171], v[184:187], v[98:101]
	v_mfma_f32_16x16x32_bf16 v[90:93], v[160:163], v[192:195], v[90:93]
	v_mfma_f32_16x16x32_bf16 v[94:97], v[168:171], v[192:195], v[94:97]
	v_mfma_f32_16x16x32_bf16 v[70:73], v[160:163], v[200:203], v[70:73]
	v_mfma_f32_16x16x32_bf16 v[74:77], v[168:171], v[200:203], v[74:77]
	v_mfma_f32_16x16x32_bf16 v[122:125], v[164:167], v[180:183], v[122:125]
	v_mfma_f32_16x16x32_bf16 v[126:129], v[172:175], v[180:183], v[126:129]
	v_mfma_f32_16x16x32_bf16 v[110:113], v[164:167], v[188:191], v[110:113]
	v_mfma_f32_16x16x32_bf16 v[98:101], v[172:175], v[188:191], v[98:101]
	v_mfma_f32_16x16x32_bf16 v[90:93], v[164:167], v[196:199], v[90:93]
	v_mfma_f32_16x16x32_bf16 v[94:97], v[172:175], v[196:199], v[94:97]
	v_mfma_f32_16x16x32_bf16 v[70:73], v[164:167], v[204:207], v[70:73]
	v_mfma_f32_16x16x32_bf16 v[74:77], v[172:175], v[204:207], v[74:77]
	s_setprio 0
	s_barrier
	ds_read_b128 v[176:179], v143 offset:16384
	ds_read_b128 v[180:183], v143 offset:17408
	ds_read_b128 v[184:187], v143 offset:18432
	ds_read_b128 v[188:191], v143 offset:19456
	ds_read_b128 v[192:195], v143 offset:20480
	ds_read_b128 v[196:199], v143 offset:21504
	ds_read_b128 v[200:203], v143 offset:22528
	ds_read_b128 v[204:207], v143 offset:23552
	s_add_i32 s48, s48, s22
	v_lshl_add_u64 v[208:209], s[16:17], 0, v[0:1]
	s_mov_b32 m0, s48
	s_nop 0
	global_load_lds_dwordx4 v0, s[16:17]
	s_add_i32 m0, s48, 0x2000
	s_add_u32 s48, s16, 0x80000
	v_lshl_add_u64 v[210:211], s[16:17], 0, v[130:131]
	s_addc_u32 s49, s17, 0
	s_add_i32 s50, s50, s22
	global_load_lds_dwordx4 v130, s[16:17]
	s_mov_b32 m0, s50
	v_lshl_add_u64 v[218:219], s[18:19], 0, v[132:133]
	global_load_lds_dwordx4 v0, s[48:49]
	s_add_i32 m0, s50, 0x2000
	s_nop 0
	global_load_lds_dwordx4 v130, s[48:49]
	v_lshl_add_u64 v[212:213], s[18:19], 0, v[134:135]
	s_mov_b32 m0, s23
	s_nop 0
	global_load_lds_dwordx4 v134, s[18:19]
	s_mov_b32 m0, s24
	s_nop 0
	global_load_lds_dwordx4 v132, s[18:19]
	s_waitcnt vmcnt(8)
	s_waitcnt lgkmcnt(0)
	s_barrier
; #define PG8_STAGE(bufoff, gbase, voff) do { _Pragma("unroll") for (int _i = 0; _i < 2; ++_i) \
;         __builtin_amdgcn_global_load_lds((const unsigned*)((const char*)(gbase) + (voff)[_i]), (PG8_LAS unsigned*)(lds + (bufoff) + ldsw + _i * 8192), 16, 0, 0); } while (0)
; #define PG8_LDA(dst, b, h) do { _Pragma("unroll") for (int m = 0; m < 4; ++m) _Pragma("unroll") for (int k = 0; k < 2; ++k) dst[m][k] = *(const PG8_LAS bf16x8*)(lds + PG8_SA(b, h) + aoff + m * 2048 + k * 1024); } while (0)
; #define PG8_LDB(dst, b, h) do { _Pragma("unroll") for (int n = 0; n < 2; ++n) _Pragma("unroll") for (int k = 0; k < 2; ++k) dst[n][k] = *(const PG8_LAS bf16x8*)(lds + PG8_SB(b, h) + boff + n * 2048 + k * 1024); } while (0)
; #define PG8_MMA(ai, bj, At, Bt) do { __builtin_amdgcn_s_setprio(1); _Pragma("unroll") for (int m = 0; m < 4; ++m) _Pragma("unroll") for (int n = 0; n < 2; ++n) _Pragma("unroll") for (int k = 0; k < 2; ++k) \
;         acc[ai][bj][m][n] = __builtin_amdgcn_mfma_f32_16x16x32_bf16(Bt[n][k], At[m][k], acc[ai][bj][m][n], 0, 0, 0); __builtin_amdgcn_s_setprio(0); } while (0)
; #define PG8_WAIT_V(n) asm volatile("s_waitcnt vmcnt(" #n ")" ::: "memory")
; #define PG8_WAIT_L(n) asm volatile("s_waitcnt lgkmcnt(" #n ")" ::: "memory")
; #define PG8_BAR __builtin_amdgcn_s_barrier()
; #define PG8_SCHED __builtin_amdgcn_sched_barrier(0)
; template <class Epi, class Sched, bool ALIGN_EPI = false, bool SP2 = false>
; __device__ __forceinline__ void gemm_phase(PG8_LAS unsigned char* lds, const Gemm g, const Sched& S, const Epi& E) {
;     ...
;             PG8_WAIT_V(8); PG8_WAIT_L(0); PG8_BAR; PG8_MMA(1, 0, At, B0); PG8_MMA(1, 1, At, B1); PG8_BAR; PG8_SCHED;
;             PG8_LDB(B0, 1, 0); PG8_LDB(B1, 1, 1); PG8_SCHED; PG8_LDA(At, 1, 0); PG8_STAGE(PG8_SA(0, 1), a2 + hstep, voffA);
;             PG8_WAIT_V(8); PG8_WAIT_L(0); PG8_BAR; PG8_MMA(0, 0, At, B0); PG8_MMA(0, 1, At, B1); PG8_BAR; PG8_SCHED;
	s_setprio 1
	s_waitcnt lgkmcnt(0)
	v_mfma_f32_16x16x32_bf16 v[50:53], v[144:147], v[176:179], v[50:53]
	v_mfma_f32_16x16x32_bf16 v[54:57], v[152:155], v[176:179], v[54:57]
	v_mfma_f32_16x16x32_bf16 v[34:37], v[144:147], v[184:187], v[34:37]
	v_mfma_f32_16x16x32_bf16 v[38:41], v[152:155], v[184:187], v[38:41]
	v_mfma_f32_16x16x32_bf16 v[18:21], v[144:147], v[192:195], v[18:21]
	v_mfma_f32_16x16x32_bf16 v[22:25], v[152:155], v[192:195], v[22:25]
	v_mfma_f32_16x16x32_bf16 v[2:5], v[144:147], v[200:203], v[2:5]
	v_mfma_f32_16x16x32_bf16 v[6:9], v[152:155], v[200:203], v[6:9]
	v_mfma_f32_16x16x32_bf16 v[50:53], v[148:151], v[180:183], v[50:53]
	v_mfma_f32_16x16x32_bf16 v[54:57], v[156:159], v[180:183], v[54:57]
	v_mfma_f32_16x16x32_bf16 v[34:37], v[148:151], v[188:191], v[34:37]
	v_mfma_f32_16x16x32_bf16 v[38:41], v[156:159], v[188:191], v[38:41]
	v_mfma_f32_16x16x32_bf16 v[18:21], v[148:151], v[196:199], v[18:21]
	v_mfma_f32_16x16x32_bf16 v[22:25], v[156:159], v[196:199], v[22:25]
	v_mfma_f32_16x16x32_bf16 v[2:5], v[148:151], v[204:207], v[2:5]
	v_mfma_f32_16x16x32_bf16 v[6:9], v[156:159], v[204:207], v[6:9]
	s_setprio 0
	s_setprio 1
	v_mfma_f32_16x16x32_bf16 v[62:65], v[160:163], v[176:179], v[62:65]
	v_mfma_f32_16x16x32_bf16 v[66:69], v[168:171], v[176:179], v[66:69]
	v_mfma_f32_16x16x32_bf16 v[42:45], v[160:163], v[184:187], v[42:45]
	v_mfma_f32_16x16x32_bf16 v[46:49], v[168:171], v[184:187], v[46:49]
	v_mfma_f32_16x16x32_bf16 v[26:29], v[160:163], v[192:195], v[26:29]
	v_mfma_f32_16x16x32_bf16 v[30:33], v[168:171], v[192:195], v[30:33]
	v_mfma_f32_16x16x32_bf16 v[10:13], v[160:163], v[200:203], v[10:13]
	v_mfma_f32_16x16x32_bf16 v[14:17], v[168:171], v[200:203], v[14:17]
	v_mfma_f32_16x16x32_bf16 v[62:65], v[164:167], v[180:183], v[62:65]
	v_mfma_f32_16x16x32_bf16 v[66:69], v[172:175], v[180:183], v[66:69]
	v_mfma_f32_16x16x32_bf16 v[42:45], v[164:167], v[188:191], v[42:45]
	v_mfma_f32_16x16x32_bf16 v[46:49], v[172:175], v[188:191], v[46:49]
	v_mfma_f32_16x16x32_bf16 v[26:29], v[164:167], v[196:199], v[26:29]
	v_mfma_f32_16x16x32_bf16 v[30:33], v[172:175], v[196:199], v[30:33]
	v_mfma_f32_16x16x32_bf16 v[10:13], v[164:167], v[204:207], v[10:13]
	v_mfma_f32_16x16x32_bf16 v[14:17], v[172:175], v[204:207], v[14:17]
	s_setprio 0
	s_barrier
	ds_read_b128 v[176:179], v143 offset:32768
	ds_read_b128 v[180:183], v143 offset:33792
	ds_read_b128 v[184:187], v143 offset:34816
	ds_read_b128 v[188:191], v143 offset:35840
	ds_read_b128 v[192:195], v143 offset:36864
	ds_read_b128 v[196:199], v143 offset:37888
	ds_read_b128 v[200:203], v143 offset:38912
	ds_read_b128 v[204:207], v143 offset:39936
	s_add_i32 s48, 0, 0x18000
	s_add_i32 s49, 0, 0x1c000
	v_add_u32_e32 v156, s48, v140
	v_add_u32_e32 v172, s49, v140
	ds_read_b128 v[144:147], v156
	ds_read_b128 v[148:151], v156 offset:1024
	ds_read_b128 v[152:155], v156 offset:2048
	ds_read_b128 v[156:159], v156 offset:3072
	ds_read_b128 v[160:163], v172
	ds_read_b128 v[164:167], v172 offset:1024
	ds_read_b128 v[168:171], v172 offset:2048
	ds_read_b128 v[172:175], v172 offset:3072
	s_add_u32 s18, s18, 0x80000
	s_addc_u32 s19, s19, 0
	s_mov_b32 m0, s25
	s_nop 0
	global_load_lds_dwordx4 v134, s[18:19]
	s_mov_b32 m0, s26
	s_nop 0
	global_load_lds_dwordx4 v132, s[18:19]
	s_waitcnt vmcnt(8)
	s_waitcnt lgkmcnt(0)
	s_barrier
	s_setprio 1
	s_waitcnt lgkmcnt(0)
	v_mfma_f32_16x16x32_bf16 v[114:117], v[144:147], v[176:179], v[114:117]
	v_mfma_f32_16x16x32_bf16 v[118:121], v[152:155], v[176:179], v[118:121]
	v_mfma_f32_16x16x32_bf16 v[102:105], v[144:147], v[184:187], v[102:105]
	v_mfma_f32_16x16x32_bf16 v[106:109], v[152:155], v[184:187], v[106:109]
	v_mfma_f32_16x16x32_bf16 v[86:89], v[144:147], v[192:195], v[86:89]
	v_mfma_f32_16x16x32_bf16 v[82:85], v[152:155], v[192:195], v[82:85]
	v_mfma_f32_16x16x32_bf16 v[78:81], v[144:147], v[200:203], v[78:81]
	v_mfma_f32_16x16x32_bf16 v[58:61], v[152:155], v[200:203], v[58:61]
	v_mfma_f32_16x16x32_bf16 v[114:117], v[148:151], v[180:183], v[114:117]
	v_mfma_f32_16x16x32_bf16 v[118:121], v[156:159], v[180:183], v[118:121]
	v_mfma_f32_16x16x32_bf16 v[102:105], v[148:151], v[188:191], v[102:105]
	v_mfma_f32_16x16x32_bf16 v[106:109], v[156:159], v[188:191], v[106:109]
	v_mfma_f32_16x16x32_bf16 v[86:89], v[148:151], v[196:199], v[86:89]
	v_mfma_f32_16x16x32_bf16 v[82:85], v[156:159], v[196:199], v[82:85]
	v_mfma_f32_16x16x32_bf16 v[78:81], v[148:151], v[204:207], v[78:81]
	v_mfma_f32_16x16x32_bf16 v[58:61], v[156:159], v[204:207], v[58:61]
	s_setprio 0
	s_setprio 1
	v_mfma_f32_16x16x32_bf16 v[122:125], v[160:163], v[176:179], v[122:125]
	v_mfma_f32_16x16x32_bf16 v[126:129], v[168:171], v[176:179], v[126:129]
	v_mfma_f32_16x16x32_bf16 v[110:113], v[160:163], v[184:187], v[110:113]
	v_mfma_f32_16x16x32_bf16 v[98:101], v[168:171], v[184:187], v[98:101]
	v_mfma_f32_16x16x32_bf16 v[90:93], v[160:163], v[192:195], v[90:93]
	v_mfma_f32_16x16x32_bf16 v[94:97], v[168:171], v[192:195], v[94:97]
	v_mfma_f32_16x16x32_bf16 v[70:73], v[160:163], v[200:203], v[70:73]
	v_mfma_f32_16x16x32_bf16 v[74:77], v[168:171], v[200:203], v[74:77]
	v_mfma_f32_16x16x32_bf16 v[122:125], v[164:167], v[180:183], v[122:125]
	v_mfma_f32_16x16x32_bf16 v[126:129], v[172:175], v[180:183], v[126:129]
	v_mfma_f32_16x16x32_bf16 v[110:113], v[164:167], v[188:191], v[110:113]
	v_mfma_f32_16x16x32_bf16 v[98:101], v[172:175], v[188:191], v[98:101]
	v_mfma_f32_16x16x32_bf16 v[90:93], v[164:167], v[196:199], v[90:93]
	v_mfma_f32_16x16x32_bf16 v[94:97], v[172:175], v[196:199], v[94:97]
	v_mfma_f32_16x16x32_bf16 v[70:73], v[164:167], v[204:207], v[70:73]
	v_mfma_f32_16x16x32_bf16 v[74:77], v[172:175], v[204:207], v[74:77]
	s_setprio 0
	s_barrier
; #define PG8_STAGE(bufoff, gbase, voff) do { _Pragma("unroll") for (int _i = 0; _i < 2; ++_i) \
;         __builtin_amdgcn_global_load_lds((const unsigned*)((const char*)(gbase) + (voff)[_i]), (PG8_LAS unsigned*)(lds + (bufoff) + ldsw + _i * 8192), 16, 0, 0); } while (0)
; #define PG8_LDA(dst, b, h) do { _Pragma("unroll") for (int m = 0; m < 4; ++m) _Pragma("unroll") for (int k = 0; k < 2; ++k) dst[m][k] = *(const PG8_LAS bf16x8*)(lds + PG8_SA(b, h) + aoff + m * 2048 + k * 1024); } while (0)
; #define PG8_MMA(ai, bj, At, Bt) do { __builtin_amdgcn_s_setprio(1); _Pragma("unroll") for (int m = 0; m < 4; ++m) _Pragma("unroll") for (int n = 0; n < 2; ++n) _Pragma("unroll") for (int k = 0; k < 2; ++k) \
;         acc[ai][bj][m][n] = __builtin_amdgcn_mfma_f32_16x16x32_bf16(Bt[n][k], At[m][k], acc[ai][bj][m][n], 0, 0, 0); __builtin_amdgcn_s_setprio(0); } while (0)
; #define PG8_WAIT_V(n) asm volatile("s_waitcnt vmcnt(" #n ")" ::: "memory")
; #define PG8_WAIT_L(n) asm volatile("s_waitcnt lgkmcnt(" #n ")" ::: "memory")
; #define PG8_BAR __builtin_amdgcn_s_barrier()
; #define PG8_SCHED __builtin_amdgcn_sched_barrier(0)
; template <class Epi, class Sched, bool ALIGN_EPI = false, bool SP2 = false>
; __device__ __forceinline__ void gemm_phase(PG8_LAS unsigned char* lds, const Gemm g, const Sched& S, const Epi& E) {
;     ...
;             PG8_LDA(At, 1, 1); PG8_STAGE(PG8_SB(1, 0), b3, voffB); PG8_STAGE(PG8_SB(1, 1), b3 + hstep, voffB); PG8_STAGE(PG8_SA(1, 0), a3, voffA);
;             PG8_WAIT_V(8); PG8_WAIT_L(0); PG8_BAR; PG8_MMA(1, 0, At, B0); PG8_MMA(1, 1, At, B1); PG8_BAR; PG8_SCHED;
	ds_read_b128 v[176:179], v143 offset:49152
	ds_read_b128 v[180:183], v143 offset:50176
	ds_read_b128 v[184:187], v143 offset:51200
	ds_read_b128 v[188:191], v143 offset:52224
	ds_read_b128 v[192:195], v143 offset:53248
	ds_read_b128 v[196:199], v143 offset:54272
	ds_read_b128 v[200:203], v143 offset:55296
	ds_read_b128 v[204:207], v143 offset:56320
	s_add_i32 s18, s48, s22
	v_lshl_add_u64 v[208:209], v[208:209], 0, s[78:79]
	s_mov_b32 m0, s18
	s_nop 0
	global_load_lds_dwordx4 v[208:209], off
	s_add_i32 m0, s18, 0x2000
	s_add_u32 s16, s16, 0x80080
	v_lshl_add_u64 v[208:209], v[210:211], 0, s[78:79]
	s_addc_u32 s17, s17, 0
	s_add_i32 s18, s49, s22
	global_load_lds_dwordx4 v[208:209], off
	s_mov_b32 m0, s18
	s_nop 0
	global_load_lds_dwordx4 v0, s[16:17]
	s_add_i32 m0, s18, 0x2000
	s_nop 0
	global_load_lds_dwordx4 v130, s[16:17]
	v_lshl_add_u64 v[208:209], v[212:213], 0, s[78:79]
	s_mov_b32 m0, s27
	s_nop 0
	global_load_lds_dwordx4 v[208:209], off
	v_lshl_add_u64 v[208:209], v[218:219], 0, s[78:79]
	s_mov_b32 m0, s28
	s_nop 0
	global_load_lds_dwordx4 v[208:209], off
	s_waitcnt vmcnt(8)
	s_waitcnt lgkmcnt(0)
	s_barrier
	s_setprio 1
	s_waitcnt lgkmcnt(0)
	v_mfma_f32_16x16x32_bf16 v[50:53], v[144:147], v[176:179], v[50:53]
	v_mfma_f32_16x16x32_bf16 v[54:57], v[152:155], v[176:179], v[54:57]
	v_mfma_f32_16x16x32_bf16 v[34:37], v[144:147], v[184:187], v[34:37]
	v_mfma_f32_16x16x32_bf16 v[38:41], v[152:155], v[184:187], v[38:41]
	v_mfma_f32_16x16x32_bf16 v[18:21], v[144:147], v[192:195], v[18:21]
	v_mfma_f32_16x16x32_bf16 v[22:25], v[152:155], v[192:195], v[22:25]
	v_mfma_f32_16x16x32_bf16 v[2:5], v[144:147], v[200:203], v[2:5]
	v_mfma_f32_16x16x32_bf16 v[6:9], v[152:155], v[200:203], v[6:9]
	v_mfma_f32_16x16x32_bf16 v[50:53], v[148:151], v[180:183], v[50:53]
	v_mfma_f32_16x16x32_bf16 v[54:57], v[156:159], v[180:183], v[54:57]
	v_mfma_f32_16x16x32_bf16 v[34:37], v[148:151], v[188:191], v[34:37]
	v_mfma_f32_16x16x32_bf16 v[38:41], v[156:159], v[188:191], v[38:41]
	v_mfma_f32_16x16x32_bf16 v[18:21], v[148:151], v[196:199], v[18:21]
	v_mfma_f32_16x16x32_bf16 v[22:25], v[156:159], v[196:199], v[22:25]
	v_mfma_f32_16x16x32_bf16 v[2:5], v[148:151], v[204:207], v[2:5]
	v_mfma_f32_16x16x32_bf16 v[6:9], v[156:159], v[204:207], v[6:9]
	s_setprio 0
	s_setprio 1
	v_mfma_f32_16x16x32_bf16 v[62:65], v[160:163], v[176:179], v[62:65]
	v_mfma_f32_16x16x32_bf16 v[66:69], v[168:171], v[176:179], v[66:69]
	v_mfma_f32_16x16x32_bf16 v[42:45], v[160:163], v[184:187], v[42:45]
	v_mfma_f32_16x16x32_bf16 v[46:49], v[168:171], v[184:187], v[46:49]
	v_mfma_f32_16x16x32_bf16 v[26:29], v[160:163], v[192:195], v[26:29]
	v_mfma_f32_16x16x32_bf16 v[30:33], v[168:171], v[192:195], v[30:33]
	v_mfma_f32_16x16x32_bf16 v[10:13], v[160:163], v[200:203], v[10:13]
	v_mfma_f32_16x16x32_bf16 v[14:17], v[168:171], v[200:203], v[14:17]
	v_mfma_f32_16x16x32_bf16 v[62:65], v[164:167], v[180:183], v[62:65]
	v_mfma_f32_16x16x32_bf16 v[66:69], v[172:175], v[180:183], v[66:69]
	v_mfma_f32_16x16x32_bf16 v[42:45], v[164:167], v[188:191], v[42:45]
	v_mfma_f32_16x16x32_bf16 v[46:49], v[172:175], v[188:191], v[46:49]
	v_mfma_f32_16x16x32_bf16 v[26:29], v[164:167], v[196:199], v[26:29]
	v_mfma_f32_16x16x32_bf16 v[30:33], v[172:175], v[196:199], v[30:33]
	v_mfma_f32_16x16x32_bf16 v[10:13], v[164:167], v[204:207], v[10:13]
	v_mfma_f32_16x16x32_bf16 v[14:17], v[172:175], v[204:207], v[14:17]
	s_setprio 0
	s_barrier
	s_add_i32 s47, s47, 2
	s_add_u32 s45, s45, 0x100
	s_addc_u32 s46, s46, 0
	s_add_u32 s14, s14, 0x100
	s_addc_u32 s15, s15, 0
	s_cmp_gt_u32 s47, 29
	s_cbranch_scc0 .LBB0_436
	s_and_b64 vcc, exec, s[4:5]
	v_readlane_b32 s47, v254, 33
	s_cbranch_vccz .LBB0_439
	s_barrier

; #define PG8_STAGE(bufoff, gbase, voff) do { _Pragma("unroll") for (int _i = 0; _i < 2; ++_i) \
;         __builtin_amdgcn_global_load_lds((const unsigned*)((const char*)(gbase) + (voff)[_i]), (PG8_LAS unsigned*)(lds + (bufoff) + ldsw + _i * 8192), 16, 0, 0); } while (0)
; #define PG8_LDA(dst, b, h) do { _Pragma("unroll") for (int m = 0; m < 4; ++m) _Pragma("unroll") for (int k = 0; k < 2; ++k) dst[m][k] = *(const PG8_LAS bf16x8*)(lds + PG8_SA(b, h) + aoff + m * 2048 + k * 1024); } while (0)
; #define PG8_LDB(dst, b, h) do { _Pragma("unroll") for (int n = 0; n < 2; ++n) _Pragma("unroll") for (int k = 0; k < 2; ++k) dst[n][k] = *(const PG8_LAS bf16x8*)(lds + PG8_SB(b, h) + boff + n * 2048 + k * 1024); } while (0)
; #define PG8_MMA(ai, bj, At, Bt) do { __builtin_amdgcn_s_setprio(1); _Pragma("unroll") for (int m = 0; m < 4; ++m) _Pragma("unroll") for (int n = 0; n < 2; ++n) _Pragma("unroll") for (int k = 0; k < 2; ++k) \
;         acc[ai][bj][m][n] = __builtin_amdgcn_mfma_f32_16x16x32_bf16(Bt[n][k], At[m][k], acc[ai][bj][m][n], 0, 0, 0); __builtin_amdgcn_s_setprio(0); } while (0)
; #define PG8_WAIT_V(n) asm volatile("s_waitcnt vmcnt(" #n ")" ::: "memory")
; #define PG8_WAIT_L(n) asm volatile("s_waitcnt lgkmcnt(" #n ")" ::: "memory")
; #define PG8_BAR __builtin_amdgcn_s_barrier()
; #define PG8_SCHED __builtin_amdgcn_sched_barrier(0)
; template <class Epi, class Sched, bool ALIGN_EPI = false, bool SP2 = false>
; __device__ __forceinline__ void gemm_phase(PG8_LAS unsigned char* lds, const Gemm g, const Sched& S, const Epi& E) {
;     ...
;             PG8_LDB(B0, 0, 0); PG8_LDB(B1, 0, 1); PG8_SCHED; PG8_LDA(At, 0, 0); PG8_STAGE(PG8_SA(1, 1), a1 + hstep, voffA);
;             PG8_WAIT_V(8); PG8_WAIT_L(0); PG8_BAR; PG8_MMA(0, 0, At, B0); PG8_MMA(0, 1, At, B1); PG8_BAR; PG8_SCHED;
;             PG8_LDA(At, 0, 1); PG8_STAGE(PG8_SB(0, 0), b2, voffB); PG8_STAGE(PG8_SB(0, 1), b2 + hstep, voffB); PG8_STAGE(PG8_SA(0, 0), a2, voffA);
.LBB0_458:
	ds_read_b128 v[174:177], v188
	ds_read_b128 v[178:181], v188 offset:1024
	ds_read_b128 v[182:185], v188 offset:2048
	ds_read_b128 v[190:193], v188 offset:3072
	ds_read_b128 v[194:197], v188 offset:4096
	ds_read_b128 v[198:201], v188 offset:5120
	ds_read_b128 v[202:205], v188 offset:6144
	ds_read_b128 v[206:209], v188 offset:7168
	s_add_i32 s51, s14, 2
	s_add_u32 s52, s12, 0x80
	s_addc_u32 s15, s13, 0
	s_add_i32 s54, 0, 0x10000
	s_cmp_eq_u32 s36, s14
	s_cselect_b32 s15, s9, s15
	s_cselect_b32 s14, s8, s52
	s_cselect_b32 s53, s11, s45
	s_cselect_b32 s52, s10, s44
	s_add_i32 s55, 0, 0x14000
	v_add_u32_e32 v142, s54, v159
	v_add_u32_e32 v170, s55, v159
	ds_read_b128 v[130:133], v142
	ds_read_b128 v[134:137], v142 offset:1024
	ds_read_b128 v[138:141], v142 offset:2048
	ds_read_b128 v[142:145], v142 offset:3072
	ds_read_b128 v[146:149], v170
	ds_read_b128 v[150:153], v170 offset:1024
	ds_read_b128 v[154:157], v170 offset:2048
	ds_read_b128 v[170:173], v170 offset:3072
	s_add_i32 m0, s20, 0xc000
	s_nop 0
	global_load_lds_dwordx4 v168, s[12:13]
	s_add_i32 m0, s20, 0xe000
	s_nop 0
	global_load_lds_dwordx4 v166, s[12:13]
	s_waitcnt vmcnt(8)
	s_waitcnt lgkmcnt(0)
	s_barrier
	s_setprio 1
	s_waitcnt lgkmcnt(0)
	v_mfma_f32_16x16x32_bf16 v[126:129], v[130:133], v[174:177], v[126:129]
	v_mfma_f32_16x16x32_bf16 v[122:125], v[138:141], v[174:177], v[122:125]
	v_mfma_f32_16x16x32_bf16 v[110:113], v[130:133], v[182:185], v[110:113]
	v_mfma_f32_16x16x32_bf16 v[106:109], v[138:141], v[182:185], v[106:109]
	v_mfma_f32_16x16x32_bf16 v[94:97], v[130:133], v[194:197], v[94:97]
	v_mfma_f32_16x16x32_bf16 v[90:93], v[138:141], v[194:197], v[90:93]
	v_mfma_f32_16x16x32_bf16 v[78:81], v[130:133], v[202:205], v[78:81]
	v_mfma_f32_16x16x32_bf16 v[74:77], v[138:141], v[202:205], v[74:77]
	v_mfma_f32_16x16x32_bf16 v[126:129], v[134:137], v[178:181], v[126:129]
	v_mfma_f32_16x16x32_bf16 v[122:125], v[142:145], v[178:181], v[122:125]
	v_mfma_f32_16x16x32_bf16 v[110:113], v[134:137], v[190:193], v[110:113]
	v_mfma_f32_16x16x32_bf16 v[106:109], v[142:145], v[190:193], v[106:109]
	v_mfma_f32_16x16x32_bf16 v[94:97], v[134:137], v[198:201], v[94:97]
	v_mfma_f32_16x16x32_bf16 v[90:93], v[142:145], v[198:201], v[90:93]
	v_mfma_f32_16x16x32_bf16 v[78:81], v[134:137], v[206:209], v[78:81]
	v_mfma_f32_16x16x32_bf16 v[74:77], v[142:145], v[206:209], v[74:77]
	s_setprio 0
	s_setprio 1
	v_mfma_f32_16x16x32_bf16 v[118:121], v[146:149], v[174:177], v[118:121]
	v_mfma_f32_16x16x32_bf16 v[114:117], v[154:157], v[174:177], v[114:117]
	v_mfma_f32_16x16x32_bf16 v[102:105], v[146:149], v[182:185], v[102:105]
	v_mfma_f32_16x16x32_bf16 v[98:101], v[154:157], v[182:185], v[98:101]
	v_mfma_f32_16x16x32_bf16 v[86:89], v[146:149], v[194:197], v[86:89]
	v_mfma_f32_16x16x32_bf16 v[82:85], v[154:157], v[194:197], v[82:85]
	v_mfma_f32_16x16x32_bf16 v[70:73], v[146:149], v[202:205], v[70:73]
	v_mfma_f32_16x16x32_bf16 v[66:69], v[154:157], v[202:205], v[66:69]
	v_mfma_f32_16x16x32_bf16 v[118:121], v[150:153], v[178:181], v[118:121]
	v_mfma_f32_16x16x32_bf16 v[114:117], v[170:173], v[178:181], v[114:117]
	v_mfma_f32_16x16x32_bf16 v[102:105], v[150:153], v[190:193], v[102:105]
	v_mfma_f32_16x16x32_bf16 v[98:101], v[170:173], v[190:193], v[98:101]
	v_mfma_f32_16x16x32_bf16 v[86:89], v[150:153], v[198:201], v[86:89]
	v_mfma_f32_16x16x32_bf16 v[82:85], v[170:173], v[198:201], v[82:85]
	v_mfma_f32_16x16x32_bf16 v[70:73], v[150:153], v[206:209], v[70:73]
	v_mfma_f32_16x16x32_bf16 v[66:69], v[170:173], v[206:209], v[66:69]
	s_setprio 0
	s_barrier
	ds_read_b128 v[174:177], v188 offset:16384
	ds_read_b128 v[178:181], v188 offset:17408
	ds_read_b128 v[182:185], v188 offset:18432
	ds_read_b128 v[190:193], v188 offset:19456
	ds_read_b128 v[194:197], v188 offset:20480
	ds_read_b128 v[198:201], v188 offset:21504
	ds_read_b128 v[202:205], v188 offset:22528
	ds_read_b128 v[206:209], v188 offset:23552
	s_add_i32 s54, s54, s19
	v_lshl_add_u64 v[210:211], s[52:53], 0, v[0:1]
	s_mov_b32 m0, s54
	s_nop 0
	global_load_lds_dwordx4 v0, s[52:53]
	s_add_i32 m0, s54, 0x2000
	v_lshl_add_u64 v[212:213], s[52:53], 0, v[160:161]
	s_add_u32 s52, s52, s86
	s_addc_u32 s53, s53, 0
	s_add_i32 s54, s55, s19
	global_load_lds_dwordx4 v[212:213], off
	v_lshl_add_u64 v[218:219], s[52:53], 0, v[0:1]
	s_mov_b32 m0, s54
	v_lshl_add_u64 v[220:221], s[52:53], 0, v[160:161]
	global_load_lds_dwordx4 v0, s[52:53]
	s_add_i32 m0, s54, 0x2000
	v_lshl_add_u64 v[222:223], s[14:15], 0, v[162:163]
	global_load_lds_dwordx4 v160, s[52:53]
	s_mov_b32 m0, s20
	v_lshl_add_u64 v[224:225], s[14:15], 0, v[164:165]
	global_load_lds_dwordx4 v162, s[14:15]
	s_mov_b32 m0, s21
	s_nop 0
	global_load_lds_dwordx4 v164, s[14:15]
	s_waitcnt vmcnt(8)
	s_waitcnt lgkmcnt(0)
	s_barrier
; #define PG8_STAGE(bufoff, gbase, voff) do { _Pragma("unroll") for (int _i = 0; _i < 2; ++_i) \
;         __builtin_amdgcn_global_load_lds((const unsigned*)((const char*)(gbase) + (voff)[_i]), (PG8_LAS unsigned*)(lds + (bufoff) + ldsw + _i * 8192), 16, 0, 0); } while (0)
; #define PG8_LDA(dst, b, h) do { _Pragma("unroll") for (int m = 0; m < 4; ++m) _Pragma("unroll") for (int k = 0; k < 2; ++k) dst[m][k] = *(const PG8_LAS bf16x8*)(lds + PG8_SA(b, h) + aoff + m * 2048 + k * 1024); } while (0)
; #define PG8_LDB(dst, b, h) do { _Pragma("unroll") for (int n = 0; n < 2; ++n) _Pragma("unroll") for (int k = 0; k < 2; ++k) dst[n][k] = *(const PG8_LAS bf16x8*)(lds + PG8_SB(b, h) + boff + n * 2048 + k * 1024); } while (0)
; #define PG8_MMA(ai, bj, At, Bt) do { __builtin_amdgcn_s_setprio(1); _Pragma("unroll") for (int m = 0; m < 4; ++m) _Pragma("unroll") for (int n = 0; n < 2; ++n) _Pragma("unroll") for (int k = 0; k < 2; ++k) \
;         acc[ai][bj][m][n] = __builtin_amdgcn_mfma_f32_16x16x32_bf16(Bt[n][k], At[m][k], acc[ai][bj][m][n], 0, 0, 0); __builtin_amdgcn_s_setprio(0); } while (0)
; #define PG8_WAIT_V(n) asm volatile("s_waitcnt vmcnt(" #n ")" ::: "memory")
; #define PG8_WAIT_L(n) asm volatile("s_waitcnt lgkmcnt(" #n ")" ::: "memory")
; #define PG8_BAR __builtin_amdgcn_s_barrier()
; #define PG8_SCHED __builtin_amdgcn_sched_barrier(0)
; template <class Epi, class Sched, bool ALIGN_EPI = false, bool SP2 = false>
; __device__ __forceinline__ void gemm_phase(PG8_LAS unsigned char* lds, const Gemm g, const Sched& S, const Epi& E) {
;     ...
;             PG8_WAIT_V(8); PG8_WAIT_L(0); PG8_BAR; PG8_MMA(1, 0, At, B0); PG8_MMA(1, 1, At, B1); PG8_BAR; PG8_SCHED;
;             PG8_LDB(B0, 1, 0); PG8_LDB(B1, 1, 1); PG8_SCHED; PG8_LDA(At, 1, 0); PG8_STAGE(PG8_SA(0, 1), a2 + hstep, voffA);
;             PG8_WAIT_V(8); PG8_WAIT_L(0); PG8_BAR; PG8_MMA(0, 0, At, B0); PG8_MMA(0, 1, At, B1); PG8_BAR; PG8_SCHED;
	s_setprio 1
	s_waitcnt lgkmcnt(0)
	v_mfma_f32_16x16x32_bf16 v[62:65], v[130:133], v[174:177], v[62:65]
	v_mfma_f32_16x16x32_bf16 v[58:61], v[138:141], v[174:177], v[58:61]
	v_mfma_f32_16x16x32_bf16 v[42:45], v[130:133], v[182:185], v[42:45]
	v_mfma_f32_16x16x32_bf16 v[38:41], v[138:141], v[182:185], v[38:41]
	v_mfma_f32_16x16x32_bf16 v[22:25], v[130:133], v[194:197], v[22:25]
	v_mfma_f32_16x16x32_bf16 v[18:21], v[138:141], v[194:197], v[18:21]
	v_mfma_f32_16x16x32_bf16 v[6:9], v[130:133], v[202:205], v[6:9]
	v_mfma_f32_16x16x32_bf16 v[2:5], v[138:141], v[202:205], v[2:5]
	v_mfma_f32_16x16x32_bf16 v[62:65], v[134:137], v[178:181], v[62:65]
	v_mfma_f32_16x16x32_bf16 v[58:61], v[142:145], v[178:181], v[58:61]
	v_mfma_f32_16x16x32_bf16 v[42:45], v[134:137], v[190:193], v[42:45]
	v_mfma_f32_16x16x32_bf16 v[38:41], v[142:145], v[190:193], v[38:41]
	v_mfma_f32_16x16x32_bf16 v[22:25], v[134:137], v[198:201], v[22:25]
	v_mfma_f32_16x16x32_bf16 v[18:21], v[142:145], v[198:201], v[18:21]
	v_mfma_f32_16x16x32_bf16 v[6:9], v[134:137], v[206:209], v[6:9]
	v_mfma_f32_16x16x32_bf16 v[2:5], v[142:145], v[206:209], v[2:5]
	s_setprio 0
	s_setprio 1
	v_mfma_f32_16x16x32_bf16 v[54:57], v[146:149], v[174:177], v[54:57]
	v_mfma_f32_16x16x32_bf16 v[50:53], v[154:157], v[174:177], v[50:53]
	v_mfma_f32_16x16x32_bf16 v[34:37], v[146:149], v[182:185], v[34:37]
	v_mfma_f32_16x16x32_bf16 v[46:49], v[154:157], v[182:185], v[46:49]
	v_mfma_f32_16x16x32_bf16 v[30:33], v[146:149], v[194:197], v[30:33]
	v_mfma_f32_16x16x32_bf16 v[26:29], v[154:157], v[194:197], v[26:29]
	v_mfma_f32_16x16x32_bf16 v[14:17], v[146:149], v[202:205], v[14:17]
	v_mfma_f32_16x16x32_bf16 v[10:13], v[154:157], v[202:205], v[10:13]
	v_mfma_f32_16x16x32_bf16 v[54:57], v[150:153], v[178:181], v[54:57]
	v_mfma_f32_16x16x32_bf16 v[50:53], v[170:173], v[178:181], v[50:53]
	v_mfma_f32_16x16x32_bf16 v[34:37], v[150:153], v[190:193], v[34:37]
	v_mfma_f32_16x16x32_bf16 v[46:49], v[170:173], v[190:193], v[46:49]
	v_mfma_f32_16x16x32_bf16 v[30:33], v[150:153], v[198:201], v[30:33]
	v_mfma_f32_16x16x32_bf16 v[26:29], v[170:173], v[198:201], v[26:29]
	v_mfma_f32_16x16x32_bf16 v[14:17], v[150:153], v[206:209], v[14:17]
	v_mfma_f32_16x16x32_bf16 v[10:13], v[170:173], v[206:209], v[10:13]
	s_setprio 0
	s_barrier
	ds_read_b128 v[174:177], v188 offset:32768
	ds_read_b128 v[178:181], v188 offset:33792
	ds_read_b128 v[182:185], v188 offset:34816
	ds_read_b128 v[190:193], v188 offset:35840
	ds_read_b128 v[194:197], v188 offset:36864
	ds_read_b128 v[198:201], v188 offset:37888
	ds_read_b128 v[202:205], v188 offset:38912
	ds_read_b128 v[206:209], v188 offset:39936
	s_add_i32 s52, 0, 0x18000
	s_add_i32 s53, 0, 0x1c000
	v_add_u32_e32 v142, s52, v159
	v_add_u32_e32 v170, s53, v159
	ds_read_b128 v[130:133], v142
	ds_read_b128 v[134:137], v142 offset:1024
	ds_read_b128 v[138:141], v142 offset:2048
	ds_read_b128 v[142:145], v142 offset:3072
	ds_read_b128 v[146:149], v170
	ds_read_b128 v[150:153], v170 offset:1024
	ds_read_b128 v[154:157], v170 offset:2048
	ds_read_b128 v[170:173], v170 offset:3072
	s_add_u32 s14, s14, s86
	s_addc_u32 s15, s15, 0
	s_mov_b32 m0, s22
	s_nop 0
	global_load_lds_dwordx4 v162, s[14:15]
	s_mov_b32 m0, s23
	s_nop 0
	global_load_lds_dwordx4 v164, s[14:15]
	s_waitcnt vmcnt(8)
	s_waitcnt lgkmcnt(0)
	s_barrier
	s_setprio 1
	s_waitcnt lgkmcnt(0)
	v_mfma_f32_16x16x32_bf16 v[126:129], v[130:133], v[174:177], v[126:129]
	v_mfma_f32_16x16x32_bf16 v[122:125], v[138:141], v[174:177], v[122:125]
	v_mfma_f32_16x16x32_bf16 v[110:113], v[130:133], v[182:185], v[110:113]
	v_mfma_f32_16x16x32_bf16 v[106:109], v[138:141], v[182:185], v[106:109]
	v_mfma_f32_16x16x32_bf16 v[94:97], v[130:133], v[194:197], v[94:97]
	v_mfma_f32_16x16x32_bf16 v[90:93], v[138:141], v[194:197], v[90:93]
	v_mfma_f32_16x16x32_bf16 v[78:81], v[130:133], v[202:205], v[78:81]
	v_mfma_f32_16x16x32_bf16 v[74:77], v[138:141], v[202:205], v[74:77]
	v_mfma_f32_16x16x32_bf16 v[126:129], v[134:137], v[178:181], v[126:129]
	v_mfma_f32_16x16x32_bf16 v[122:125], v[142:145], v[178:181], v[122:125]
	v_mfma_f32_16x16x32_bf16 v[110:113], v[134:137], v[190:193], v[110:113]
	v_mfma_f32_16x16x32_bf16 v[106:109], v[142:145], v[190:193], v[106:109]
	v_mfma_f32_16x16x32_bf16 v[94:97], v[134:137], v[198:201], v[94:97]
	v_mfma_f32_16x16x32_bf16 v[90:93], v[142:145], v[198:201], v[90:93]
	v_mfma_f32_16x16x32_bf16 v[78:81], v[134:137], v[206:209], v[78:81]
	v_mfma_f32_16x16x32_bf16 v[74:77], v[142:145], v[206:209], v[74:77]
	s_setprio 0
	s_setprio 1
	v_mfma_f32_16x16x32_bf16 v[118:121], v[146:149], v[174:177], v[118:121]
	v_mfma_f32_16x16x32_bf16 v[114:117], v[154:157], v[174:177], v[114:117]
	v_mfma_f32_16x16x32_bf16 v[102:105], v[146:149], v[182:185], v[102:105]
	v_mfma_f32_16x16x32_bf16 v[98:101], v[154:157], v[182:185], v[98:101]
	v_mfma_f32_16x16x32_bf16 v[86:89], v[146:149], v[194:197], v[86:89]
	v_mfma_f32_16x16x32_bf16 v[82:85], v[154:157], v[194:197], v[82:85]
	v_mfma_f32_16x16x32_bf16 v[70:73], v[146:149], v[202:205], v[70:73]
	v_mfma_f32_16x16x32_bf16 v[66:69], v[154:157], v[202:205], v[66:69]
	v_mfma_f32_16x16x32_bf16 v[118:121], v[150:153], v[178:181], v[118:121]
	v_mfma_f32_16x16x32_bf16 v[114:117], v[170:173], v[178:181], v[114:117]
	v_mfma_f32_16x16x32_bf16 v[102:105], v[150:153], v[190:193], v[102:105]
	v_mfma_f32_16x16x32_bf16 v[98:101], v[170:173], v[190:193], v[98:101]
	v_mfma_f32_16x16x32_bf16 v[86:89], v[150:153], v[198:201], v[86:89]
	v_mfma_f32_16x16x32_bf16 v[82:85], v[170:173], v[198:201], v[82:85]
	v_mfma_f32_16x16x32_bf16 v[70:73], v[150:153], v[206:209], v[70:73]
	v_mfma_f32_16x16x32_bf16 v[66:69], v[170:173], v[206:209], v[66:69]
	s_setprio 0
	s_barrier
; #define PG8_STAGE(bufoff, gbase, voff) do { _Pragma("unroll") for (int _i = 0; _i < 2; ++_i) \
;         __builtin_amdgcn_global_load_lds((const unsigned*)((const char*)(gbase) + (voff)[_i]), (PG8_LAS unsigned*)(lds + (bufoff) + ldsw + _i * 8192), 16, 0, 0); } while (0)
; #define PG8_LDA(dst, b, h) do { _Pragma("unroll") for (int m = 0; m < 4; ++m) _Pragma("unroll") for (int k = 0; k < 2; ++k) dst[m][k] = *(const PG8_LAS bf16x8*)(lds + PG8_SA(b, h) + aoff + m * 2048 + k * 1024); } while (0)
; #define PG8_MMA(ai, bj, At, Bt) do { __builtin_amdgcn_s_setprio(1); _Pragma("unroll") for (int m = 0; m < 4; ++m) _Pragma("unroll") for (int n = 0; n < 2; ++n) _Pragma("unroll") for (int k = 0; k < 2; ++k) \
;         acc[ai][bj][m][n] = __builtin_amdgcn_mfma_f32_16x16x32_bf16(Bt[n][k], At[m][k], acc[ai][bj][m][n], 0, 0, 0); __builtin_amdgcn_s_setprio(0); } while (0)
; #define PG8_WAIT_V(n) asm volatile("s_waitcnt vmcnt(" #n ")" ::: "memory")
; #define PG8_WAIT_L(n) asm volatile("s_waitcnt lgkmcnt(" #n ")" ::: "memory")
; #define PG8_BAR __builtin_amdgcn_s_barrier()
; #define PG8_SCHED __builtin_amdgcn_sched_barrier(0)
; template <class Epi, class Sched, bool ALIGN_EPI = false, bool SP2 = false>
; __device__ __forceinline__ void gemm_phase(PG8_LAS unsigned char* lds, const Gemm g, const Sched& S, const Epi& E) {
;     ...
;             PG8_LDA(At, 1, 1); PG8_STAGE(PG8_SB(1, 0), b3, voffB); PG8_STAGE(PG8_SB(1, 1), b3 + hstep, voffB); PG8_STAGE(PG8_SA(1, 0), a3, voffA);
;             PG8_WAIT_V(8); PG8_WAIT_L(0); PG8_BAR; PG8_MMA(1, 0, At, B0); PG8_MMA(1, 1, At, B1); PG8_BAR; PG8_SCHED;
	ds_read_b128 v[174:177], v188 offset:49152
	ds_read_b128 v[178:181], v188 offset:50176
	ds_read_b128 v[182:185], v188 offset:51200
	ds_read_b128 v[190:193], v188 offset:52224
	ds_read_b128 v[194:197], v188 offset:53248
	ds_read_b128 v[198:201], v188 offset:54272
	ds_read_b128 v[202:205], v188 offset:55296
	ds_read_b128 v[206:209], v188 offset:56320
	s_add_i32 s14, s52, s19
	v_lshl_add_u64 v[210:211], v[210:211], 0, s[78:79]
	s_mov_b32 m0, s14
	s_nop 0
	global_load_lds_dwordx4 v[210:211], off
	v_lshl_add_u64 v[210:211], v[212:213], 0, s[78:79]
	s_add_i32 m0, s14, 0x2000
	s_add_i32 s14, s53, s19
	global_load_lds_dwordx4 v[210:211], off
	v_lshl_add_u64 v[210:211], v[218:219], 0, s[78:79]
	s_mov_b32 m0, s14
	s_nop 0
	global_load_lds_dwordx4 v[210:211], off
	v_lshl_add_u64 v[210:211], v[220:221], 0, s[78:79]
	s_add_i32 m0, s14, 0x2000
	s_nop 0
	global_load_lds_dwordx4 v[210:211], off
	v_lshl_add_u64 v[210:211], v[222:223], 0, s[78:79]
	s_mov_b32 m0, s24
	s_nop 0
	global_load_lds_dwordx4 v[210:211], off
	v_lshl_add_u64 v[210:211], v[224:225], 0, s[78:79]
	s_mov_b32 m0, s25
	s_nop 0
	global_load_lds_dwordx4 v[210:211], off
	s_waitcnt vmcnt(8)
	s_waitcnt lgkmcnt(0)
	s_barrier
	s_setprio 1
	s_waitcnt lgkmcnt(0)
	v_mfma_f32_16x16x32_bf16 v[62:65], v[130:133], v[174:177], v[62:65]
	v_mfma_f32_16x16x32_bf16 v[58:61], v[138:141], v[174:177], v[58:61]
	v_mfma_f32_16x16x32_bf16 v[42:45], v[130:133], v[182:185], v[42:45]
	v_mfma_f32_16x16x32_bf16 v[38:41], v[138:141], v[182:185], v[38:41]
	v_mfma_f32_16x16x32_bf16 v[22:25], v[130:133], v[194:197], v[22:25]
	v_mfma_f32_16x16x32_bf16 v[18:21], v[138:141], v[194:197], v[18:21]
	v_mfma_f32_16x16x32_bf16 v[6:9], v[130:133], v[202:205], v[6:9]
	v_mfma_f32_16x16x32_bf16 v[2:5], v[138:141], v[202:205], v[2:5]
	v_mfma_f32_16x16x32_bf16 v[62:65], v[134:137], v[178:181], v[62:65]
	v_mfma_f32_16x16x32_bf16 v[58:61], v[142:145], v[178:181], v[58:61]
	v_mfma_f32_16x16x32_bf16 v[42:45], v[134:137], v[190:193], v[42:45]
	v_mfma_f32_16x16x32_bf16 v[38:41], v[142:145], v[190:193], v[38:41]
	v_mfma_f32_16x16x32_bf16 v[22:25], v[134:137], v[198:201], v[22:25]
	v_mfma_f32_16x16x32_bf16 v[18:21], v[142:145], v[198:201], v[18:21]
	v_mfma_f32_16x16x32_bf16 v[6:9], v[134:137], v[206:209], v[6:9]
	v_mfma_f32_16x16x32_bf16 v[2:5], v[142:145], v[206:209], v[2:5]
	s_setprio 0
	s_setprio 1
	v_mfma_f32_16x16x32_bf16 v[54:57], v[146:149], v[174:177], v[54:57]
	v_mfma_f32_16x16x32_bf16 v[50:53], v[154:157], v[174:177], v[50:53]
	v_mfma_f32_16x16x32_bf16 v[34:37], v[146:149], v[182:185], v[34:37]
	v_mfma_f32_16x16x32_bf16 v[46:49], v[154:157], v[182:185], v[46:49]
	v_mfma_f32_16x16x32_bf16 v[30:33], v[146:149], v[194:197], v[30:33]
	v_mfma_f32_16x16x32_bf16 v[26:29], v[154:157], v[194:197], v[26:29]
	v_mfma_f32_16x16x32_bf16 v[14:17], v[146:149], v[202:205], v[14:17]
	v_mfma_f32_16x16x32_bf16 v[10:13], v[154:157], v[202:205], v[10:13]
	v_mfma_f32_16x16x32_bf16 v[54:57], v[150:153], v[178:181], v[54:57]
	v_mfma_f32_16x16x32_bf16 v[50:53], v[170:173], v[178:181], v[50:53]
	v_mfma_f32_16x16x32_bf16 v[34:37], v[150:153], v[190:193], v[34:37]
	v_mfma_f32_16x16x32_bf16 v[46:49], v[170:173], v[190:193], v[46:49]
	v_mfma_f32_16x16x32_bf16 v[30:33], v[150:153], v[198:201], v[30:33]
	v_mfma_f32_16x16x32_bf16 v[26:29], v[170:173], v[198:201], v[26:29]
	v_mfma_f32_16x16x32_bf16 v[14:17], v[150:153], v[206:209], v[14:17]
	v_mfma_f32_16x16x32_bf16 v[10:13], v[170:173], v[206:209], v[10:13]
	s_setprio 0
	s_barrier
	s_add_u32 s44, s44, 0x100
	s_addc_u32 s45, s45, 0
	s_add_u32 s12, s12, 0x100
	s_addc_u32 s13, s13, 0
	s_cmp_ge_u32 s51, s29
	s_mov_b32 s14, s51
	s_cbranch_scc0 .LBB0_458
	s_and_b64 vcc, exec, s[6:7]
	s_cbranch_vccz .LBB0_461
	s_barrier

; #define PG8_STAGE(bufoff, gbase, voff) do { _Pragma("unroll") for (int _i = 0; _i < 2; ++_i) \
;         __builtin_amdgcn_global_load_lds((const unsigned*)((const char*)(gbase) + (voff)[_i]), (PG8_LAS unsigned*)(lds + (bufoff) + ldsw + _i * 8192), 16, 0, 0); } while (0)
; #define PG8_LDA(dst, b, h) do { _Pragma("unroll") for (int m = 0; m < 4; ++m) _Pragma("unroll") for (int k = 0; k < 2; ++k) dst[m][k] = *(const PG8_LAS bf16x8*)(lds + PG8_SA(b, h) + aoff + m * 2048 + k * 1024); } while (0)
; #define PG8_LDB(dst, b, h) do { _Pragma("unroll") for (int n = 0; n < 2; ++n) _Pragma("unroll") for (int k = 0; k < 2; ++k) dst[n][k] = *(const PG8_LAS bf16x8*)(lds + PG8_SB(b, h) + boff + n * 2048 + k * 1024); } while (0)
; #define PG8_MMA(ai, bj, At, Bt) do { __builtin_amdgcn_s_setprio(1); _Pragma("unroll") for (int m = 0; m < 4; ++m) _Pragma("unroll") for (int n = 0; n < 2; ++n) _Pragma("unroll") for (int k = 0; k < 2; ++k) \
;         acc[ai][bj][m][n] = __builtin_amdgcn_mfma_f32_16x16x32_bf16(Bt[n][k], At[m][k], acc[ai][bj][m][n], 0, 0, 0); __builtin_amdgcn_s_setprio(0); } while (0)
; #define PG8_WAIT_V(n) asm volatile("s_waitcnt vmcnt(" #n ")" ::: "memory")
; #define PG8_WAIT_L(n) asm volatile("s_waitcnt lgkmcnt(" #n ")" ::: "memory")
; #define PG8_BAR __builtin_amdgcn_s_barrier()
; #define PG8_SCHED __builtin_amdgcn_sched_barrier(0)
; template <class Epi, class Sched, bool ALIGN_EPI = false, bool SP2 = false>
; __device__ __forceinline__ void gemm_phase(PG8_LAS unsigned char* lds, const Gemm g, const Sched& S, const Epi& E) {
;     ...
;             PG8_LDB(B0, 0, 0); PG8_LDB(B1, 0, 1); PG8_SCHED; PG8_LDA(At, 0, 0); PG8_STAGE(PG8_SA(1, 1), a1 + hstep, voffA);
;             PG8_WAIT_V(8); PG8_WAIT_L(0); PG8_BAR; PG8_MMA(0, 0, At, B0); PG8_MMA(0, 1, At, B1); PG8_BAR; PG8_SCHED;
;             PG8_LDA(At, 0, 1); PG8_STAGE(PG8_SB(0, 0), b2, voffB); PG8_STAGE(PG8_SB(0, 1), b2 + hstep, voffB); PG8_STAGE(PG8_SA(0, 0), a2, voffA);
.LBB0_571:
	ds_read_b128 v[176:179], v143
	ds_read_b128 v[180:183], v143 offset:1024
	ds_read_b128 v[184:187], v143 offset:2048
	ds_read_b128 v[188:191], v143 offset:3072
	ds_read_b128 v[192:195], v143 offset:4096
	ds_read_b128 v[196:199], v143 offset:5120
	ds_read_b128 v[200:203], v143 offset:6144
	ds_read_b128 v[204:207], v143 offset:7168
	s_add_u32 s16, s14, 0xfff80080
	s_addc_u32 s17, s15, -1
	s_add_i32 s48, 0, 0x10000
	s_cmp_eq_u32 s47, 28
	s_cselect_b32 s19, s9, s17
	s_cselect_b32 s18, s43, s16
	s_cselect_b32 s17, s7, s46
	s_cselect_b32 s16, s44, s45
	s_add_i32 s50, 0, 0x14000
	v_add_u32_e32 v156, s48, v140
	v_add_u32_e32 v172, s50, v140
	ds_read_b128 v[144:147], v156
	ds_read_b128 v[148:151], v156 offset:1024
	ds_read_b128 v[152:155], v156 offset:2048
	ds_read_b128 v[156:159], v156 offset:3072
	ds_read_b128 v[160:163], v172
	ds_read_b128 v[164:167], v172 offset:1024
	ds_read_b128 v[168:171], v172 offset:2048
	ds_read_b128 v[172:175], v172 offset:3072
	s_add_i32 m0, s23, 0xc000
	s_nop 0
	global_load_lds_dwordx4 v138, s[14:15]
	s_add_i32 m0, s23, 0xe000
	s_nop 0
	global_load_lds_dwordx4 v136, s[14:15]
	s_waitcnt vmcnt(8)
	s_waitcnt lgkmcnt(0)
	s_barrier
	s_setprio 1
	s_waitcnt lgkmcnt(0)
	v_mfma_f32_16x16x32_bf16 v[114:117], v[144:147], v[176:179], v[114:117]
	v_mfma_f32_16x16x32_bf16 v[118:121], v[152:155], v[176:179], v[118:121]
	v_mfma_f32_16x16x32_bf16 v[102:105], v[144:147], v[184:187], v[102:105]
	v_mfma_f32_16x16x32_bf16 v[106:109], v[152:155], v[184:187], v[106:109]
	v_mfma_f32_16x16x32_bf16 v[82:85], v[144:147], v[192:195], v[82:85]
	v_mfma_f32_16x16x32_bf16 v[86:89], v[152:155], v[192:195], v[86:89]
	v_mfma_f32_16x16x32_bf16 v[66:69], v[144:147], v[200:203], v[66:69]
	v_mfma_f32_16x16x32_bf16 v[70:73], v[152:155], v[200:203], v[70:73]
	v_mfma_f32_16x16x32_bf16 v[114:117], v[148:151], v[180:183], v[114:117]
	v_mfma_f32_16x16x32_bf16 v[118:121], v[156:159], v[180:183], v[118:121]
	v_mfma_f32_16x16x32_bf16 v[102:105], v[148:151], v[188:191], v[102:105]
	v_mfma_f32_16x16x32_bf16 v[106:109], v[156:159], v[188:191], v[106:109]
	v_mfma_f32_16x16x32_bf16 v[82:85], v[148:151], v[196:199], v[82:85]
	v_mfma_f32_16x16x32_bf16 v[86:89], v[156:159], v[196:199], v[86:89]
	v_mfma_f32_16x16x32_bf16 v[66:69], v[148:151], v[204:207], v[66:69]
	v_mfma_f32_16x16x32_bf16 v[70:73], v[156:159], v[204:207], v[70:73]
	s_setprio 0
	s_setprio 1
	v_mfma_f32_16x16x32_bf16 v[122:125], v[160:163], v[176:179], v[122:125]
	v_mfma_f32_16x16x32_bf16 v[126:129], v[168:171], v[176:179], v[126:129]
	v_mfma_f32_16x16x32_bf16 v[110:113], v[160:163], v[184:187], v[110:113]
	v_mfma_f32_16x16x32_bf16 v[98:101], v[168:171], v[184:187], v[98:101]
	v_mfma_f32_16x16x32_bf16 v[94:97], v[160:163], v[192:195], v[94:97]
	v_mfma_f32_16x16x32_bf16 v[90:93], v[168:171], v[192:195], v[90:93]
	v_mfma_f32_16x16x32_bf16 v[78:81], v[160:163], v[200:203], v[78:81]
	v_mfma_f32_16x16x32_bf16 v[74:77], v[168:171], v[200:203], v[74:77]
	v_mfma_f32_16x16x32_bf16 v[122:125], v[164:167], v[180:183], v[122:125]
	v_mfma_f32_16x16x32_bf16 v[126:129], v[172:175], v[180:183], v[126:129]
	v_mfma_f32_16x16x32_bf16 v[110:113], v[164:167], v[188:191], v[110:113]
	v_mfma_f32_16x16x32_bf16 v[98:101], v[172:175], v[188:191], v[98:101]
	v_mfma_f32_16x16x32_bf16 v[94:97], v[164:167], v[196:199], v[94:97]
	v_mfma_f32_16x16x32_bf16 v[90:93], v[172:175], v[196:199], v[90:93]
	v_mfma_f32_16x16x32_bf16 v[78:81], v[164:167], v[204:207], v[78:81]
	v_mfma_f32_16x16x32_bf16 v[74:77], v[172:175], v[204:207], v[74:77]
	s_setprio 0
	s_barrier
	ds_read_b128 v[176:179], v143 offset:16384
	ds_read_b128 v[180:183], v143 offset:17408
	ds_read_b128 v[184:187], v143 offset:18432
	ds_read_b128 v[188:191], v143 offset:19456
	ds_read_b128 v[192:195], v143 offset:20480
	ds_read_b128 v[196:199], v143 offset:21504
	ds_read_b128 v[200:203], v143 offset:22528
	ds_read_b128 v[204:207], v143 offset:23552
	s_add_i32 s48, s48, s22
	v_lshl_add_u64 v[208:209], s[16:17], 0, v[0:1]
	s_mov_b32 m0, s48
	s_nop 0
	global_load_lds_dwordx4 v0, s[16:17]
	s_add_i32 m0, s48, 0x2000
	s_add_u32 s48, s16, 0x80000
	v_lshl_add_u64 v[210:211], s[16:17], 0, v[130:131]
	s_addc_u32 s49, s17, 0
	s_add_i32 s50, s50, s22
	global_load_lds_dwordx4 v130, s[16:17]
	s_mov_b32 m0, s50
	v_lshl_add_u64 v[218:219], s[18:19], 0, v[132:133]
	global_load_lds_dwordx4 v0, s[48:49]
	s_add_i32 m0, s50, 0x2000
	s_nop 0
	global_load_lds_dwordx4 v130, s[48:49]
	v_lshl_add_u64 v[212:213], s[18:19], 0, v[134:135]
	s_mov_b32 m0, s23
	s_nop 0
	global_load_lds_dwordx4 v134, s[18:19]
	s_mov_b32 m0, s24
	s_nop 0
	global_load_lds_dwordx4 v132, s[18:19]
	s_waitcnt vmcnt(8)
	s_waitcnt lgkmcnt(0)
	s_barrier
; #define PG8_STAGE(bufoff, gbase, voff) do { _Pragma("unroll") for (int _i = 0; _i < 2; ++_i) \
;         __builtin_amdgcn_global_load_lds((const unsigned*)((const char*)(gbase) + (voff)[_i]), (PG8_LAS unsigned*)(lds + (bufoff) + ldsw + _i * 8192), 16, 0, 0); } while (0)
; #define PG8_LDA(dst, b, h) do { _Pragma("unroll") for (int m = 0; m < 4; ++m) _Pragma("unroll") for (int k = 0; k < 2; ++k) dst[m][k] = *(const PG8_LAS bf16x8*)(lds + PG8_SA(b, h) + aoff + m * 2048 + k * 1024); } while (0)
; #define PG8_LDB(dst, b, h) do { _Pragma("unroll") for (int n = 0; n < 2; ++n) _Pragma("unroll") for (int k = 0; k < 2; ++k) dst[n][k] = *(const PG8_LAS bf16x8*)(lds + PG8_SB(b, h) + boff + n * 2048 + k * 1024); } while (0)
; #define PG8_MMA(ai, bj, At, Bt) do { __builtin_amdgcn_s_setprio(1); _Pragma("unroll") for (int m = 0; m < 4; ++m) _Pragma("unroll") for (int n = 0; n < 2; ++n) _Pragma("unroll") for (int k = 0; k < 2; ++k) \
;         acc[ai][bj][m][n] = __builtin_amdgcn_mfma_f32_16x16x32_bf16(Bt[n][k], At[m][k], acc[ai][bj][m][n], 0, 0, 0); __builtin_amdgcn_s_setprio(0); } while (0)
; #define PG8_WAIT_V(n) asm volatile("s_waitcnt vmcnt(" #n ")" ::: "memory")
; #define PG8_WAIT_L(n) asm volatile("s_waitcnt lgkmcnt(" #n ")" ::: "memory")
; #define PG8_BAR __builtin_amdgcn_s_barrier()
; #define PG8_SCHED __builtin_amdgcn_sched_barrier(0)
; template <class Epi, class Sched, bool ALIGN_EPI = false, bool SP2 = false>
; __device__ __forceinline__ void gemm_phase(PG8_LAS unsigned char* lds, const Gemm g, const Sched& S, const Epi& E) {
;     ...
;             PG8_WAIT_V(8); PG8_WAIT_L(0); PG8_BAR; PG8_MMA(1, 0, At, B0); PG8_MMA(1, 1, At, B1); PG8_BAR; PG8_SCHED;
;             PG8_LDB(B0, 1, 0); PG8_LDB(B1, 1, 1); PG8_SCHED; PG8_LDA(At, 1, 0); PG8_STAGE(PG8_SA(0, 1), a2 + hstep, voffA);
;             PG8_WAIT_V(8); PG8_WAIT_L(0); PG8_BAR; PG8_MMA(0, 0, At, B0); PG8_MMA(0, 1, At, B1); PG8_BAR; PG8_SCHED;
	s_setprio 1
	s_waitcnt lgkmcnt(0)
	v_mfma_f32_16x16x32_bf16 v[50:53], v[144:147], v[176:179], v[50:53]
	v_mfma_f32_16x16x32_bf16 v[54:57], v[152:155], v[176:179], v[54:57]
	v_mfma_f32_16x16x32_bf16 v[34:37], v[144:147], v[184:187], v[34:37]
	v_mfma_f32_16x16x32_bf16 v[38:41], v[152:155], v[184:187], v[38:41]
	v_mfma_f32_16x16x32_bf16 v[18:21], v[144:147], v[192:195], v[18:21]
	v_mfma_f32_16x16x32_bf16 v[22:25], v[152:155], v[192:195], v[22:25]
	v_mfma_f32_16x16x32_bf16 v[2:5], v[144:147], v[200:203], v[2:5]
	v_mfma_f32_16x16x32_bf16 v[6:9], v[152:155], v[200:203], v[6:9]
	v_mfma_f32_16x16x32_bf16 v[50:53], v[148:151], v[180:183], v[50:53]
	v_mfma_f32_16x16x32_bf16 v[54:57], v[156:159], v[180:183], v[54:57]
	v_mfma_f32_16x16x32_bf16 v[34:37], v[148:151], v[188:191], v[34:37]
	v_mfma_f32_16x16x32_bf16 v[38:41], v[156:159], v[188:191], v[38:41]
	v_mfma_f32_16x16x32_bf16 v[18:21], v[148:151], v[196:199], v[18:21]
	v_mfma_f32_16x16x32_bf16 v[22:25], v[156:159], v[196:199], v[22:25]
	v_mfma_f32_16x16x32_bf16 v[2:5], v[148:151], v[204:207], v[2:5]
	v_mfma_f32_16x16x32_bf16 v[6:9], v[156:159], v[204:207], v[6:9]
	s_setprio 0
	s_setprio 1
	v_mfma_f32_16x16x32_bf16 v[62:65], v[160:163], v[176:179], v[62:65]
	v_mfma_f32_16x16x32_bf16 v[58:61], v[168:171], v[176:179], v[58:61]
	v_mfma_f32_16x16x32_bf16 v[42:45], v[160:163], v[184:187], v[42:45]
	v_mfma_f32_16x16x32_bf16 v[46:49], v[168:171], v[184:187], v[46:49]
	v_mfma_f32_16x16x32_bf16 v[30:33], v[160:163], v[192:195], v[30:33]
	v_mfma_f32_16x16x32_bf16 v[26:29], v[168:171], v[192:195], v[26:29]
	v_mfma_f32_16x16x32_bf16 v[14:17], v[160:163], v[200:203], v[14:17]
	v_mfma_f32_16x16x32_bf16 v[10:13], v[168:171], v[200:203], v[10:13]
	v_mfma_f32_16x16x32_bf16 v[62:65], v[164:167], v[180:183], v[62:65]
	v_mfma_f32_16x16x32_bf16 v[58:61], v[172:175], v[180:183], v[58:61]
	v_mfma_f32_16x16x32_bf16 v[42:45], v[164:167], v[188:191], v[42:45]
	v_mfma_f32_16x16x32_bf16 v[46:49], v[172:175], v[188:191], v[46:49]
	v_mfma_f32_16x16x32_bf16 v[30:33], v[164:167], v[196:199], v[30:33]
	v_mfma_f32_16x16x32_bf16 v[26:29], v[172:175], v[196:199], v[26:29]
	v_mfma_f32_16x16x32_bf16 v[14:17], v[164:167], v[204:207], v[14:17]
	v_mfma_f32_16x16x32_bf16 v[10:13], v[172:175], v[204:207], v[10:13]
	s_setprio 0
	s_barrier
	ds_read_b128 v[176:179], v143 offset:32768
	ds_read_b128 v[180:183], v143 offset:33792
	ds_read_b128 v[184:187], v143 offset:34816
	ds_read_b128 v[188:191], v143 offset:35840
	ds_read_b128 v[192:195], v143 offset:36864
	ds_read_b128 v[196:199], v143 offset:37888
	ds_read_b128 v[200:203], v143 offset:38912
	ds_read_b128 v[204:207], v143 offset:39936
	s_add_i32 s48, 0, 0x18000
	s_add_i32 s49, 0, 0x1c000
	v_add_u32_e32 v156, s48, v140
	v_add_u32_e32 v172, s49, v140
	ds_read_b128 v[144:147], v156
	ds_read_b128 v[148:151], v156 offset:1024
	ds_read_b128 v[152:155], v156 offset:2048
	ds_read_b128 v[156:159], v156 offset:3072
	ds_read_b128 v[160:163], v172
	ds_read_b128 v[164:167], v172 offset:1024
	ds_read_b128 v[168:171], v172 offset:2048
	ds_read_b128 v[172:175], v172 offset:3072
	s_add_u32 s18, s18, 0x80000
	s_addc_u32 s19, s19, 0
	s_mov_b32 m0, s25
	s_nop 0
	global_load_lds_dwordx4 v134, s[18:19]
	s_mov_b32 m0, s26
	s_nop 0
	global_load_lds_dwordx4 v132, s[18:19]
	s_waitcnt vmcnt(8)
	s_waitcnt lgkmcnt(0)
	s_barrier
	s_setprio 1
	s_waitcnt lgkmcnt(0)
	v_mfma_f32_16x16x32_bf16 v[114:117], v[144:147], v[176:179], v[114:117]
	v_mfma_f32_16x16x32_bf16 v[118:121], v[152:155], v[176:179], v[118:121]
	v_mfma_f32_16x16x32_bf16 v[102:105], v[144:147], v[184:187], v[102:105]
	v_mfma_f32_16x16x32_bf16 v[106:109], v[152:155], v[184:187], v[106:109]
	v_mfma_f32_16x16x32_bf16 v[82:85], v[144:147], v[192:195], v[82:85]
	v_mfma_f32_16x16x32_bf16 v[86:89], v[152:155], v[192:195], v[86:89]
	v_mfma_f32_16x16x32_bf16 v[66:69], v[144:147], v[200:203], v[66:69]
	v_mfma_f32_16x16x32_bf16 v[70:73], v[152:155], v[200:203], v[70:73]
	v_mfma_f32_16x16x32_bf16 v[114:117], v[148:151], v[180:183], v[114:117]
	v_mfma_f32_16x16x32_bf16 v[118:121], v[156:159], v[180:183], v[118:121]
	v_mfma_f32_16x16x32_bf16 v[102:105], v[148:151], v[188:191], v[102:105]
	v_mfma_f32_16x16x32_bf16 v[106:109], v[156:159], v[188:191], v[106:109]
	v_mfma_f32_16x16x32_bf16 v[82:85], v[148:151], v[196:199], v[82:85]
	v_mfma_f32_16x16x32_bf16 v[86:89], v[156:159], v[196:199], v[86:89]
	v_mfma_f32_16x16x32_bf16 v[66:69], v[148:151], v[204:207], v[66:69]
	v_mfma_f32_16x16x32_bf16 v[70:73], v[156:159], v[204:207], v[70:73]
	s_setprio 0
	s_setprio 1
	v_mfma_f32_16x16x32_bf16 v[122:125], v[160:163], v[176:179], v[122:125]
	v_mfma_f32_16x16x32_bf16 v[126:129], v[168:171], v[176:179], v[126:129]
	v_mfma_f32_16x16x32_bf16 v[110:113], v[160:163], v[184:187], v[110:113]
	v_mfma_f32_16x16x32_bf16 v[98:101], v[168:171], v[184:187], v[98:101]
	v_mfma_f32_16x16x32_bf16 v[94:97], v[160:163], v[192:195], v[94:97]
	v_mfma_f32_16x16x32_bf16 v[90:93], v[168:171], v[192:195], v[90:93]
	v_mfma_f32_16x16x32_bf16 v[78:81], v[160:163], v[200:203], v[78:81]
	v_mfma_f32_16x16x32_bf16 v[74:77], v[168:171], v[200:203], v[74:77]
	v_mfma_f32_16x16x32_bf16 v[122:125], v[164:167], v[180:183], v[122:125]
	v_mfma_f32_16x16x32_bf16 v[126:129], v[172:175], v[180:183], v[126:129]
	v_mfma_f32_16x16x32_bf16 v[110:113], v[164:167], v[188:191], v[110:113]
	v_mfma_f32_16x16x32_bf16 v[98:101], v[172:175], v[188:191], v[98:101]
	v_mfma_f32_16x16x32_bf16 v[94:97], v[164:167], v[196:199], v[94:97]
	v_mfma_f32_16x16x32_bf16 v[90:93], v[172:175], v[196:199], v[90:93]
	v_mfma_f32_16x16x32_bf16 v[78:81], v[164:167], v[204:207], v[78:81]
	v_mfma_f32_16x16x32_bf16 v[74:77], v[172:175], v[204:207], v[74:77]
	s_setprio 0
	s_barrier
; #define PG8_STAGE(bufoff, gbase, voff) do { _Pragma("unroll") for (int _i = 0; _i < 2; ++_i) \
;         __builtin_amdgcn_global_load_lds((const unsigned*)((const char*)(gbase) + (voff)[_i]), (PG8_LAS unsigned*)(lds + (bufoff) + ldsw + _i * 8192), 16, 0, 0); } while (0)
; #define PG8_LDA(dst, b, h) do { _Pragma("unroll") for (int m = 0; m < 4; ++m) _Pragma("unroll") for (int k = 0; k < 2; ++k) dst[m][k] = *(const PG8_LAS bf16x8*)(lds + PG8_SA(b, h) + aoff + m * 2048 + k * 1024); } while (0)
; #define PG8_MMA(ai, bj, At, Bt) do { __builtin_amdgcn_s_setprio(1); _Pragma("unroll") for (int m = 0; m < 4; ++m) _Pragma("unroll") for (int n = 0; n < 2; ++n) _Pragma("unroll") for (int k = 0; k < 2; ++k) \
;         acc[ai][bj][m][n] = __builtin_amdgcn_mfma_f32_16x16x32_bf16(Bt[n][k], At[m][k], acc[ai][bj][m][n], 0, 0, 0); __builtin_amdgcn_s_setprio(0); } while (0)
; #define PG8_WAIT_V(n) asm volatile("s_waitcnt vmcnt(" #n ")" ::: "memory")
; #define PG8_WAIT_L(n) asm volatile("s_waitcnt lgkmcnt(" #n ")" ::: "memory")
; #define PG8_BAR __builtin_amdgcn_s_barrier()
; #define PG8_SCHED __builtin_amdgcn_sched_barrier(0)
; template <class Epi, class Sched, bool ALIGN_EPI = false, bool SP2 = false>
; __device__ __forceinline__ void gemm_phase(PG8_LAS unsigned char* lds, const Gemm g, const Sched& S, const Epi& E) {
;     ...
;             PG8_LDA(At, 1, 1); PG8_STAGE(PG8_SB(1, 0), b3, voffB); PG8_STAGE(PG8_SB(1, 1), b3 + hstep, voffB); PG8_STAGE(PG8_SA(1, 0), a3, voffA);
;             PG8_WAIT_V(8); PG8_WAIT_L(0); PG8_BAR; PG8_MMA(1, 0, At, B0); PG8_MMA(1, 1, At, B1); PG8_BAR; PG8_SCHED;
	ds_read_b128 v[176:179], v143 offset:49152
	ds_read_b128 v[180:183], v143 offset:50176
	ds_read_b128 v[184:187], v143 offset:51200
	ds_read_b128 v[188:191], v143 offset:52224
	ds_read_b128 v[192:195], v143 offset:53248
	ds_read_b128 v[196:199], v143 offset:54272
	ds_read_b128 v[200:203], v143 offset:55296
	ds_read_b128 v[204:207], v143 offset:56320
	s_add_i32 s18, s48, s22
	v_lshl_add_u64 v[208:209], v[208:209], 0, s[78:79]
	s_mov_b32 m0, s18
	s_nop 0
	global_load_lds_dwordx4 v[208:209], off
	s_add_i32 m0, s18, 0x2000
	s_add_u32 s16, s16, 0x80080
	v_lshl_add_u64 v[208:209], v[210:211], 0, s[78:79]
	s_addc_u32 s17, s17, 0
	s_add_i32 s18, s49, s22
	global_load_lds_dwordx4 v[208:209], off
	s_mov_b32 m0, s18
	s_nop 0
	global_load_lds_dwordx4 v0, s[16:17]
	s_add_i32 m0, s18, 0x2000
	s_nop 0
	global_load_lds_dwordx4 v130, s[16:17]
	v_lshl_add_u64 v[208:209], v[212:213], 0, s[78:79]
	s_mov_b32 m0, s27
	s_nop 0
	global_load_lds_dwordx4 v[208:209], off
	v_lshl_add_u64 v[208:209], v[218:219], 0, s[78:79]
	s_mov_b32 m0, s28
	s_nop 0
	global_load_lds_dwordx4 v[208:209], off
	s_waitcnt vmcnt(8)
	s_waitcnt lgkmcnt(0)
	s_barrier
	s_setprio 1
	s_waitcnt lgkmcnt(0)
	v_mfma_f32_16x16x32_bf16 v[50:53], v[144:147], v[176:179], v[50:53]
	v_mfma_f32_16x16x32_bf16 v[54:57], v[152:155], v[176:179], v[54:57]
	v_mfma_f32_16x16x32_bf16 v[34:37], v[144:147], v[184:187], v[34:37]
	v_mfma_f32_16x16x32_bf16 v[38:41], v[152:155], v[184:187], v[38:41]
	v_mfma_f32_16x16x32_bf16 v[18:21], v[144:147], v[192:195], v[18:21]
	v_mfma_f32_16x16x32_bf16 v[22:25], v[152:155], v[192:195], v[22:25]
	v_mfma_f32_16x16x32_bf16 v[2:5], v[144:147], v[200:203], v[2:5]
	v_mfma_f32_16x16x32_bf16 v[6:9], v[152:155], v[200:203], v[6:9]
	v_mfma_f32_16x16x32_bf16 v[50:53], v[148:151], v[180:183], v[50:53]
	v_mfma_f32_16x16x32_bf16 v[54:57], v[156:159], v[180:183], v[54:57]
	v_mfma_f32_16x16x32_bf16 v[34:37], v[148:151], v[188:191], v[34:37]
	v_mfma_f32_16x16x32_bf16 v[38:41], v[156:159], v[188:191], v[38:41]
	v_mfma_f32_16x16x32_bf16 v[18:21], v[148:151], v[196:199], v[18:21]
	v_mfma_f32_16x16x32_bf16 v[22:25], v[156:159], v[196:199], v[22:25]
	v_mfma_f32_16x16x32_bf16 v[2:5], v[148:151], v[204:207], v[2:5]
	v_mfma_f32_16x16x32_bf16 v[6:9], v[156:159], v[204:207], v[6:9]
	s_setprio 0
	s_setprio 1
	v_mfma_f32_16x16x32_bf16 v[62:65], v[160:163], v[176:179], v[62:65]
	v_mfma_f32_16x16x32_bf16 v[58:61], v[168:171], v[176:179], v[58:61]
	v_mfma_f32_16x16x32_bf16 v[42:45], v[160:163], v[184:187], v[42:45]
	v_mfma_f32_16x16x32_bf16 v[46:49], v[168:171], v[184:187], v[46:49]
	v_mfma_f32_16x16x32_bf16 v[30:33], v[160:163], v[192:195], v[30:33]
	v_mfma_f32_16x16x32_bf16 v[26:29], v[168:171], v[192:195], v[26:29]
	v_mfma_f32_16x16x32_bf16 v[14:17], v[160:163], v[200:203], v[14:17]
	v_mfma_f32_16x16x32_bf16 v[10:13], v[168:171], v[200:203], v[10:13]
	v_mfma_f32_16x16x32_bf16 v[62:65], v[164:167], v[180:183], v[62:65]
	v_mfma_f32_16x16x32_bf16 v[58:61], v[172:175], v[180:183], v[58:61]
	v_mfma_f32_16x16x32_bf16 v[42:45], v[164:167], v[188:191], v[42:45]
	v_mfma_f32_16x16x32_bf16 v[46:49], v[172:175], v[188:191], v[46:49]
	v_mfma_f32_16x16x32_bf16 v[30:33], v[164:167], v[196:199], v[30:33]
	v_mfma_f32_16x16x32_bf16 v[26:29], v[172:175], v[196:199], v[26:29]
	v_mfma_f32_16x16x32_bf16 v[14:17], v[164:167], v[204:207], v[14:17]
	v_mfma_f32_16x16x32_bf16 v[10:13], v[172:175], v[204:207], v[10:13]
	s_setprio 0
	s_barrier
	s_add_i32 s47, s47, 2
	s_add_u32 s45, s45, 0x100
	s_addc_u32 s46, s46, 0
	s_add_u32 s14, s14, 0x100
	s_addc_u32 s15, s15, 0
	s_cmp_gt_u32 s47, 29
	s_cbranch_scc0 .LBB0_571
	s_and_b64 vcc, exec, s[4:5]
	v_readlane_b32 s47, v254, 33
	s_cbranch_vccz .LBB0_574
	s_barrier
